# P2a partial outputs stored write-through (sc1): not kept in the producer XCD's L2
# speedup vs baseline: 1.0021x; 1.0021x over previous
; #define GAS __attribute__((address_space(1)))
; #define LAS __attribute__((address_space(3)))
; __device__ __forceinline__ unsigned cvtpk(float lo, float hi) { unsigned r; asm volatile("v_cvt_pk_bf16_f32 %0, %1, %2" : "=v"(r) : "v"(lo), "v"(hi)); return r; }
; #define SBAR() __builtin_amdgcn_sched_barrier(0)
; __device__ __forceinline__ void attn_unit(const bool FINAL, const bool HN, LAS unsigned char* wl, const bf16_t* qb, const bf16_t* kb, const bf16_t* vb, int tq0, int dil, float sl, bf16x8 (&qr)[8], const bf16_t* nqb, const bf16_t* nkb, const bf16_t* nvb, int ntq0, int ndil, ...
;     ...
;     if (!FINAL) { osc = 1.0f / l_run; if (hi == 0) *(GAS f32x2*)(ml + (size_t)tq * 2) = (f32x2){m_run, l_run}; }
;     else {
;         const f32x2 s1 = st1, s2 = st2;
;         const float M = fmaxf(fmaxf(s1.x, s2.x), m_run);
;         const float a1 = __builtin_amdgcn_exp2f(s1.x - M) * s1.y, a2 = __builtin_amdgcn_exp2f(s2.x - M) * s2.y, a3 = __builtin_amdgcn_exp2f(m_run - M);
;         const float inv = 1.0f / (a1 + a2 + a3 * l_run);
;         c1 = a1 * inv; c2 = a2 * inv; osc = a3 * inv;
;     }
;     {
;         LAS unsigned char* wrow = vbuf + r32 * 256 + hi * 8; const int qx = r32 & 15;
; #pragma unroll
;         for (int d0 = 0; d0 < 4; ++d0)
; #pragma unroll
;             for (int g4 = 0; g4 < 4; ++g4) { u32x2 w; w.x = cvtpk(oT[d0][4 * g4] * osc, oT[d0][4 * g4 + 1] * osc); w.y = cvtpk(oT[d0][4 * g4 + 2] * osc, oT[d0][4 * g4 + 3] * osc);
;                 *(LAS u32x2*)(wrow + (((4 * d0 + g4) ^ qx) << 4)) = w; }
;     }
;     asm volatile("s_waitcnt lgkmcnt(0)" ::: "memory"); SBAR();
;     if (!FINAL) {
; #pragma unroll
;         for (int i = 0; i < 8; ++i) a0[i] = *(const LAS v4u*)(vbuf + (4 * i + rr0) * 256 + cs * 16);
; #pragma unroll
;         for (int i = 0; i < 8; ++i) { const int row = 4 * i + rr0, c = cs ^ (row & 15);
;             *(GAS v4u*)(part + (size_t)(tq0 + dil * row) * 128 + 8 * c) = a0[i]; }
.LBB0_414:
	s_or_b64 exec, exec, s[6:7]
	v_div_scale_f32 v64, s[6:7], v65, v65, 1.0
	v_rcp_f32_e32 v66, v64
	v_div_scale_f32 v67, vcc, 1.0, v65, 1.0
	v_fma_f32 v68, -v64, v66, 1.0
	v_fmac_f32_e32 v66, v68, v66
	v_mul_f32_e32 v68, v67, v66
	v_fma_f32 v69, -v64, v68, v67
	v_fmac_f32_e32 v68, v69, v66
	v_fma_f32 v64, -v64, v68, v67
	v_div_fmas_f32 v64, v64, v66, v68
	v_div_fixup_f32 v64, v64, v65, 1.0
	v_mul_f32_e32 v48, v64, v48
	v_mul_f32_e32 v49, v64, v49
	v_cvt_pk_bf16_f32 v48, v48, v49
	v_mul_f32_e32 v49, v64, v50
	v_mul_f32_e32 v50, v64, v51
	v_cvt_pk_bf16_f32 v49, v49, v50
	v_add_u32_e32 v50, v176, v177
	ds_write_b64 v50, v[48:49] offset:8192
	v_mul_f32_e32 v48, v64, v52
	v_mul_f32_e32 v49, v64, v53
	v_cvt_pk_bf16_f32 v48, v48, v49
	v_mul_f32_e32 v49, v64, v54
	v_mul_f32_e32 v50, v64, v55
	v_cvt_pk_bf16_f32 v49, v49, v50
	ds_write_b64 v186, v[48:49] offset:8192
	v_mul_f32_e32 v48, v64, v56
	v_mul_f32_e32 v49, v64, v57
	v_cvt_pk_bf16_f32 v48, v48, v49
	v_mul_f32_e32 v49, v64, v58
	v_mul_f32_e32 v50, v64, v59
	v_cvt_pk_bf16_f32 v49, v49, v50
	ds_write_b64 v187, v[48:49] offset:8192
	v_mul_f32_e32 v48, v64, v60
	v_mul_f32_e32 v49, v64, v61
	v_cvt_pk_bf16_f32 v48, v48, v49
	v_mul_f32_e32 v49, v64, v62
	v_mul_f32_e32 v32, v64, v32
	v_mul_f32_e32 v33, v64, v33
	v_mul_f32_e32 v50, v64, v63
	v_cvt_pk_bf16_f32 v49, v49, v50
	ds_write_b64 v188, v[48:49] offset:8192
	v_cvt_pk_bf16_f32 v32, v32, v33
	v_mul_f32_e32 v33, v64, v34
	v_mul_f32_e32 v34, v64, v35
	v_cvt_pk_bf16_f32 v33, v33, v34
	ds_write_b64 v189, v[32:33] offset:8192
	v_mul_f32_e32 v32, v64, v36
	v_mul_f32_e32 v33, v64, v37
	v_cvt_pk_bf16_f32 v32, v32, v33
	v_mul_f32_e32 v33, v64, v38
	v_mul_f32_e32 v34, v64, v39
	v_cvt_pk_bf16_f32 v33, v33, v34
	ds_write_b64 v190, v[32:33] offset:8192
	v_mul_f32_e32 v32, v64, v40
	v_mul_f32_e32 v33, v64, v41
	v_cvt_pk_bf16_f32 v32, v32, v33
	v_mul_f32_e32 v33, v64, v42
	v_mul_f32_e32 v34, v64, v43
	v_cvt_pk_bf16_f32 v33, v33, v34
	ds_write_b64 v191, v[32:33] offset:8192
	v_mul_f32_e32 v32, v64, v44
	v_mul_f32_e32 v33, v64, v45
	v_cvt_pk_bf16_f32 v32, v32, v33
	v_mul_f32_e32 v33, v64, v46
	v_mul_f32_e32 v16, v64, v16
	v_mul_f32_e32 v17, v64, v17
	v_mul_f32_e32 v34, v64, v47
	v_cvt_pk_bf16_f32 v33, v33, v34
	ds_write_b64 v192, v[32:33] offset:8192
	v_cvt_pk_bf16_f32 v16, v16, v17
	v_mul_f32_e32 v17, v64, v18
	v_mul_f32_e32 v18, v64, v19
	v_cvt_pk_bf16_f32 v17, v17, v18
	ds_write_b64 v193, v[16:17] offset:8192
	v_mul_f32_e32 v16, v64, v20
	v_mul_f32_e32 v17, v64, v21
	v_cvt_pk_bf16_f32 v16, v16, v17
	v_mul_f32_e32 v17, v64, v22
	v_mul_f32_e32 v18, v64, v23
	v_cvt_pk_bf16_f32 v17, v17, v18
	ds_write_b64 v194, v[16:17] offset:8192
	v_mul_f32_e32 v16, v64, v24
	v_mul_f32_e32 v17, v64, v25
	v_cvt_pk_bf16_f32 v16, v16, v17
	v_mul_f32_e32 v17, v64, v26
	v_mul_f32_e32 v18, v64, v27
	v_cvt_pk_bf16_f32 v17, v17, v18
	ds_write_b64 v195, v[16:17] offset:8192
	v_mul_f32_e32 v16, v64, v28
	v_mul_f32_e32 v17, v64, v29
	v_cvt_pk_bf16_f32 v16, v16, v17
	v_mul_f32_e32 v17, v64, v30
	v_mul_f32_e32 v0, v64, v0
	v_mul_f32_e32 v1, v64, v1
	v_mul_f32_e32 v18, v64, v31
	v_cvt_pk_bf16_f32 v17, v17, v18
	ds_write_b64 v196, v[16:17] offset:8192
	v_cvt_pk_bf16_f32 v0, v0, v1
	v_mul_f32_e32 v1, v64, v2
	v_mul_f32_e32 v2, v64, v3
	v_cvt_pk_bf16_f32 v1, v1, v2
	ds_write_b64 v197, v[0:1] offset:8192
	v_mul_f32_e32 v0, v64, v4
	v_mul_f32_e32 v1, v64, v5
	v_cvt_pk_bf16_f32 v0, v0, v1
	v_mul_f32_e32 v1, v64, v6
	v_mul_f32_e32 v2, v64, v7
	v_cvt_pk_bf16_f32 v1, v1, v2
	ds_write_b64 v198, v[0:1] offset:8192
	v_mul_f32_e32 v0, v64, v8
	v_mul_f32_e32 v1, v64, v9
	v_cvt_pk_bf16_f32 v0, v0, v1
	v_mul_f32_e32 v1, v64, v10
	v_mul_f32_e32 v2, v64, v11
	v_cvt_pk_bf16_f32 v1, v1, v2
	ds_write_b64 v199, v[0:1] offset:8192
	v_mul_f32_e32 v0, v64, v12
	v_mul_f32_e32 v1, v64, v13
	v_cvt_pk_bf16_f32 v0, v0, v1
	v_mul_f32_e32 v1, v64, v14
	v_mul_f32_e32 v2, v64, v15
	v_cvt_pk_bf16_f32 v1, v1, v2
	ds_write_b64 v200, v[0:1] offset:8192
	s_waitcnt lgkmcnt(0)
	v_mul_lo_u32 v32, s88, v174
	v_add_u32_e32 v32, s92, v32
	v_ashrrev_i32_e32 v33, 31, v32
	v_lshlrev_b64 v[34:35], 8, v[32:33]
	v_lshl_add_u64 v[34:35], s[16:17], 0, v[34:35]
	ds_read_b128 v[0:3], v201 offset:8192
	ds_read_b128 v[4:7], v201 offset:9216
	ds_read_b128 v[8:11], v201 offset:10240
	ds_read_b128 v[12:15], v201 offset:11264
	ds_read_b128 v[16:19], v201 offset:12288
	ds_read_b128 v[20:23], v201 offset:13312
	ds_read_b128 v[24:27], v201 offset:14336
	ds_read_b128 v[28:31], v201 offset:15360
	v_lshl_add_u64 v[34:35], v[34:35], 0, v[112:113]
	s_lshl_b32 s6, s88, 2
	s_waitcnt lgkmcnt(0)
	global_store_dwordx4 v[34:35], v[0:3], off sc1
	v_mov_b32_e32 v117, v113
	v_mov_b32_e32 v119, v113
	v_add_u32_e32 v0, s6, v32
	v_ashrrev_i32_e32 v1, 31, v0
	v_lshlrev_b64 v[2:3], 8, v[0:1]
	v_lshl_add_u64 v[2:3], s[16:17], 0, v[2:3]
	v_add_u32_e32 v0, s6, v0
	v_lshl_add_u64 v[2:3], v[2:3], 0, v[116:117]
	v_ashrrev_i32_e32 v1, 31, v0
	global_store_dwordx4 v[2:3], v[4:7], off sc1
	v_lshlrev_b64 v[2:3], 8, v[0:1]
	v_lshl_add_u64 v[2:3], s[16:17], 0, v[2:3]
	v_add_u32_e32 v0, s6, v0
	v_lshl_add_u64 v[2:3], v[2:3], 0, v[118:119]
	v_ashrrev_i32_e32 v1, 31, v0
	global_store_dwordx4 v[2:3], v[8:11], off sc1
	v_lshlrev_b64 v[2:3], 8, v[0:1]
	v_lshl_add_u64 v[2:3], s[16:17], 0, v[2:3]
	v_mov_b32_e32 v121, v113
	v_add_u32_e32 v0, s6, v0
	v_lshl_add_u64 v[2:3], v[2:3], 0, v[120:121]
	v_ashrrev_i32_e32 v1, 31, v0
	global_store_dwordx4 v[2:3], v[12:15], off sc1
	v_lshlrev_b64 v[2:3], 8, v[0:1]
	v_lshl_add_u64 v[2:3], s[16:17], 0, v[2:3]
	v_add_u32_e32 v0, s6, v0
	v_lshl_add_u64 v[2:3], v[2:3], 0, v[112:113]
	v_ashrrev_i32_e32 v1, 31, v0
	global_store_dwordx4 v[2:3], v[16:19], off sc1
	v_lshlrev_b64 v[2:3], 8, v[0:1]
	v_lshl_add_u64 v[2:3], s[16:17], 0, v[2:3]
	v_mov_b32_e32 v123, v113
	v_add_u32_e32 v0, s6, v0
	v_lshl_add_u64 v[2:3], v[2:3], 0, v[122:123]
	v_ashrrev_i32_e32 v1, 31, v0
	global_store_dwordx4 v[2:3], v[20:23], off sc1
	v_lshlrev_b64 v[2:3], 8, v[0:1]
	v_add_u32_e32 v0, s6, v0
	v_ashrrev_i32_e32 v1, 31, v0
	v_lshlrev_b64 v[0:1], 8, v[0:1]
	v_lshl_add_u64 v[2:3], s[16:17], 0, v[2:3]
	v_mov_b32_e32 v125, v113
	v_lshl_add_u64 v[0:1], s[16:17], 0, v[0:1]
	v_mov_b32_e32 v127, v113
	v_lshl_add_u64 v[2:3], v[2:3], 0, v[124:125]
	v_lshl_add_u64 v[0:1], v[0:1], 0, v[126:127]
	global_store_dwordx4 v[2:3], v[24:27], off sc1
	global_store_dwordx4 v[0:1], v[28:31], off sc1
	s_waitcnt lgkmcnt(0)
	s_andn2_b64 vcc, exec, s[46:47]
	s_mov_b64 s[6:7], -1
	s_cbranch_vccnz .LBB0_365
; #define GAS __attribute__((address_space(1)))
; #define LAS __attribute__((address_space(3)))
; __device__ __forceinline__ void at_dma_v(LAS unsigned char* vdst, const bf16_t* vbase, int tq0, int dil, int tile, int lane_) { at_dma_k(vdst, vbase, tq0, dil, tile, lane_); }
; __device__ __forceinline__ void at_dma_k(LAS unsigned char* kdst, const bf16_t* kbase, int tq0, int dil, int tile, int lane_) {
;     int lane = lane_; asm volatile("" : "+v"(lane));
;     const int r0 = lane >> 3; const unsigned c0 = (unsigned)(((lane & 7) ^ r0) << 4);
;     const int t0 = tq0 + dil * (32 * tile + r0 - 64), d8 = 8 * dil;
; #pragma unroll
;     for (int n = 0; n < 4; ++n) { int tkn = t0 + n * d8; tkn = tkn < 0 ? 0 : (tkn > SEQ - 1 ? SEQ - 1 : tkn);
;         const unsigned off = ((unsigned)tkn << 7) + c0;
;         __builtin_amdgcn_global_load_lds((const unsigned*)((const GAS char*)kbase + off), (LAS unsigned*)(kdst + n * 1024), 16, 0, 0); }
; __device__ __forceinline__ void attn_unit(const bool FINAL, const bool HN, LAS unsigned char* wl, const bf16_t* qb, const bf16_t* kb, const bf16_t* vb, int tq0, int dil, float sl, bf16x8 (&qr)[8], const bf16_t* nqb, const bf16_t* nkb, const bf16_t* nvb, int ntq0, int ndil, ...
;     ...
;     if (HN) at_dma_v(vbuf, nvb, ntq0, ndil, 0, lane);
	v_mov_b32_e32 v0, v131
	s_lshl_b32 s6, s39, 3
	v_ashrrev_i32_e32 v1, 3, v0
	v_bitop3_b32 v0, v0, v1, 7 bitop3:0x6c
	v_subrev_u32_e32 v1, 64, v1
	v_mul_lo_u32 v1, v1, s39
	v_add_u32_e32 v1, s67, v1
	v_lshlrev_b32_e32 v0, 4, v0
	v_med3_i32 v2, v1, 0, v172
	s_mov_b32 m0, s79
	v_lshl_add_u32 v2, v2, 7, v0
	v_add_u32_e32 v1, s6, v1
	global_load_lds_dwordx4 v2, s[36:37]
	v_med3_i32 v2, v1, 0, v172
	v_lshl_add_u32 v2, v2, 7, v0
	s_mov_b32 m0, s80
	v_add_u32_e32 v1, s6, v1
	global_load_lds_dwordx4 v2, s[36:37]
	v_med3_i32 v2, v1, 0, v172
	v_add_u32_e32 v1, s6, v1
	v_lshl_add_u32 v2, v2, 7, v0
	s_mov_b32 m0, s81
	v_med3_i32 v1, v1, 0, v172
	global_load_lds_dwordx4 v2, s[36:37]
	v_lshl_add_u32 v0, v1, 7, v0
	s_mov_b32 m0, s82
	s_mov_b64 s[6:7], 0
	global_load_lds_dwordx4 v0, s[36:37]
	s_branch .LBB0_365
